# GEMM accumulator zero-init per unit with 64 v_mov_b64 instead of 128 v_mov_b32
# baseline (speedup 1.0000x reference)
;     __device__ bool next(int i, Unit& u) const { if (hot) { if (i >= rounds) return false; u.pm = (c % 8) * 2 + ((c / 8) & 1); u.pn = ((c / 8) >> 1) & 3; return true; } return so.next(i, u); }
;     ...
;         const bool has_next = S.next(ui + 1, nxt);
;         const char* nA = has_next ? (const char*)g.A + (size_t)nxt.pm * tstep : cA; const char* nB = has_next ? (const char*)g.Bt + (size_t)nxt.pn * tstep : cB;
;         for (int t = 0; t < nt; t += 2) {
;             const bool last = (t == nt - 2);
;             const char* a1 = cA + (size_t)(t + 1) * kstep;
;             const char* a2 = last ? nA : cA + (size_t)(t + 2) * kstep; const char* b2 = last ? nB : cB + (size_t)(t + 2) * kstep;
;     ...
; #pragma unroll
;         for (int a = 0; a < 2; ++a)
; #pragma unroll
;             for (int b = 0; b < 2; ++b)
; #pragma unroll
;                 for (int m = 0; m < 4; ++m)
; #pragma unroll
;                     for (int n = 0; n < 2; ++n) acc[a][b][m][n] = (f32x4){0.f, 0.f, 0.f, 0.f};
.LBB0_185:
	s_ashr_i32 s53, s52, 31
	s_lshl_b64 s[16:17], s[52:53], 19
	s_add_u32 s54, s97, s16
	s_addc_u32 s55, s29, s17
	s_and_b64 s[16:17], s[38:39], exec
	s_cselect_b32 s16, s55, s1
	s_cselect_b32 s17, s54, s0
	s_ashr_i32 s51, s50, 31
	s_lshl_b64 s[42:43], s[50:51], 19
	v_readlane_b32 s51, v246, 9
	s_add_u32 s56, s51, s42
	v_readlane_b32 s42, v246, 6
	s_addc_u32 s57, s42, s43
	s_and_b64 s[42:43], s[38:39], exec
	s_cselect_b32 s51, s57, s41
	s_cselect_b32 s53, s56, s40
	s_add_u32 s0, s0, 0x40080
	s_addc_u32 s1, s1, 0
	s_add_u32 s58, s40, 0x100
	v_mov_b64_e32 v[2:3], 0
	v_mov_b64_e32 v[4:5], 0
	v_mov_b64_e32 v[6:7], 0
	v_mov_b64_e32 v[8:9], 0
	v_mov_b64_e32 v[10:11], 0
	v_mov_b64_e32 v[12:13], 0
	v_mov_b64_e32 v[14:15], 0
	v_mov_b64_e32 v[16:17], 0
	v_mov_b64_e32 v[18:19], 0
	v_mov_b64_e32 v[20:21], 0
	v_mov_b64_e32 v[22:23], 0
	v_mov_b64_e32 v[24:25], 0
	v_mov_b64_e32 v[26:27], 0
	v_mov_b64_e32 v[28:29], 0
	v_mov_b64_e32 v[30:31], 0
	v_mov_b64_e32 v[32:33], 0
	v_mov_b64_e32 v[34:35], 0
	v_mov_b64_e32 v[36:37], 0
	v_mov_b64_e32 v[38:39], 0
	v_mov_b64_e32 v[40:41], 0
	v_mov_b64_e32 v[42:43], 0
	v_mov_b64_e32 v[44:45], 0
	v_mov_b64_e32 v[46:47], 0
	v_mov_b64_e32 v[48:49], 0
	v_mov_b64_e32 v[50:51], 0
	v_mov_b64_e32 v[52:53], 0
	v_mov_b64_e32 v[54:55], 0
	v_mov_b64_e32 v[56:57], 0
	v_mov_b64_e32 v[58:59], 0
	v_mov_b64_e32 v[60:61], 0
	v_mov_b64_e32 v[62:63], 0
	v_mov_b64_e32 v[64:65], 0
	v_mov_b64_e32 v[66:67], 0
	v_mov_b64_e32 v[68:69], 0
	v_mov_b64_e32 v[70:71], 0
	v_mov_b64_e32 v[72:73], 0
	v_mov_b64_e32 v[82:83], 0
	v_mov_b64_e32 v[84:85], 0
	v_mov_b64_e32 v[86:87], 0
	v_mov_b64_e32 v[88:89], 0
	v_mov_b64_e32 v[98:99], 0
	v_mov_b64_e32 v[100:101], 0
	v_mov_b64_e32 v[102:103], 0
	v_mov_b64_e32 v[104:105], 0
	v_mov_b64_e32 v[106:107], 0
	v_mov_b64_e32 v[108:109], 0
	v_mov_b64_e32 v[110:111], 0
	v_mov_b64_e32 v[112:113], 0
	v_mov_b64_e32 v[114:115], 0
	v_mov_b64_e32 v[116:117], 0
	v_mov_b64_e32 v[118:119], 0
	v_mov_b64_e32 v[120:121], 0
	v_mov_b64_e32 v[122:123], 0
	v_mov_b64_e32 v[124:125], 0
	v_mov_b64_e32 v[126:127], 0
	v_mov_b64_e32 v[128:129], 0
	v_mov_b64_e32 v[130:131], 0
	v_mov_b64_e32 v[132:133], 0
	v_mov_b64_e32 v[134:135], 0
	v_mov_b64_e32 v[136:137], 0
	v_mov_b64_e32 v[138:139], 0
	v_mov_b64_e32 v[140:141], 0
	v_mov_b64_e32 v[142:143], 0
	v_mov_b64_e32 v[144:145], 0
	s_addc_u32 s59, s41, 0
	s_mov_b32 vcc_lo, -2

;     __device__ bool next(int i, Unit& u) const { if (hot) { if (i >= rounds) return false; u.pm = (c % 8) * 2 + ((c / 8) & 1); u.pn = ((c / 8) >> 1) & 3; return true; } return so.next(i, u); }
;     ...
;         const bool has_next = S.next(ui + 1, nxt);
;         const char* nA = has_next ? (const char*)g.A + (size_t)nxt.pm * tstep : cA; const char* nB = has_next ? (const char*)g.Bt + (size_t)nxt.pn * tstep : cB;
;         for (int t = 0; t < nt; t += 2) {
;             const bool last = (t == nt - 2);
;             const char* a1 = cA + (size_t)(t + 1) * kstep;
;             const char* a2 = last ? nA : cA + (size_t)(t + 2) * kstep; const char* b2 = last ? nB : cB + (size_t)(t + 2) * kstep;
;     ...
; #pragma unroll
;         for (int a = 0; a < 2; ++a)
; #pragma unroll
;             for (int b = 0; b < 2; ++b)
; #pragma unroll
;                 for (int m = 0; m < 4; ++m)
; #pragma unroll
;                     for (int n = 0; n < 2; ++n) acc[a][b][m][n] = (f32x4){0.f, 0.f, 0.f, 0.f};
.LBB0_442:
	s_ashr_i32 s43, s42, 31
	s_lshl_b64 s[16:17], s[42:43], 19
	s_add_u32 s44, s24, s16
	s_addc_u32 s45, s25, s17
	s_and_b64 s[16:17], s[38:39], exec
	s_cselect_b32 s16, s45, s49
	s_cselect_b32 s17, s44, s48
	s_ashr_i32 s41, s40, 31
	s_lshl_b64 s[46:47], s[40:41], 19
	s_add_u32 s46, s23, s46
	s_addc_u32 s47, s54, s47
	s_and_b64 s[52:53], s[38:39], exec
	s_cselect_b32 s41, s47, s51
	s_cselect_b32 s43, s46, s50
	s_add_u32 s48, s48, 0x40080
	s_addc_u32 s49, s49, 0
	s_add_u32 s65, s50, 0x100
	v_mov_b64_e32 v[2:3], 0
	v_mov_b64_e32 v[4:5], 0
	v_mov_b64_e32 v[6:7], 0
	v_mov_b64_e32 v[8:9], 0
	v_mov_b64_e32 v[10:11], 0
	v_mov_b64_e32 v[12:13], 0
	v_mov_b64_e32 v[14:15], 0
	v_mov_b64_e32 v[16:17], 0
	v_mov_b64_e32 v[18:19], 0
	v_mov_b64_e32 v[20:21], 0
	v_mov_b64_e32 v[22:23], 0
	v_mov_b64_e32 v[24:25], 0
	v_mov_b64_e32 v[26:27], 0
	v_mov_b64_e32 v[28:29], 0
	v_mov_b64_e32 v[30:31], 0
	v_mov_b64_e32 v[32:33], 0
	v_mov_b64_e32 v[34:35], 0
	v_mov_b64_e32 v[36:37], 0
	v_mov_b64_e32 v[38:39], 0
	v_mov_b64_e32 v[40:41], 0
	v_mov_b64_e32 v[42:43], 0
	v_mov_b64_e32 v[44:45], 0
	v_mov_b64_e32 v[46:47], 0
	v_mov_b64_e32 v[48:49], 0
	v_mov_b64_e32 v[50:51], 0
	v_mov_b64_e32 v[52:53], 0
	v_mov_b64_e32 v[54:55], 0
	v_mov_b64_e32 v[56:57], 0
	v_mov_b64_e32 v[58:59], 0
	v_mov_b64_e32 v[60:61], 0
	v_mov_b64_e32 v[62:63], 0
	v_mov_b64_e32 v[64:65], 0
	v_mov_b64_e32 v[66:67], 0
	v_mov_b64_e32 v[68:69], 0
	v_mov_b64_e32 v[70:71], 0
	v_mov_b64_e32 v[72:73], 0
	v_mov_b64_e32 v[74:75], 0
	v_mov_b64_e32 v[76:77], 0
	v_mov_b64_e32 v[78:79], 0
	v_mov_b64_e32 v[80:81], 0
	v_mov_b64_e32 v[82:83], 0
	v_mov_b64_e32 v[84:85], 0
	v_mov_b64_e32 v[86:87], 0
	v_mov_b64_e32 v[88:89], 0
	v_mov_b64_e32 v[90:91], 0
	v_mov_b64_e32 v[92:93], 0
	v_mov_b64_e32 v[94:95], 0
	v_mov_b64_e32 v[96:97], 0
	v_mov_b64_e32 v[98:99], 0
	v_mov_b64_e32 v[100:101], 0
	v_mov_b64_e32 v[102:103], 0
	v_mov_b64_e32 v[104:105], 0
	v_mov_b64_e32 v[106:107], 0
	v_mov_b64_e32 v[108:109], 0
	v_mov_b64_e32 v[110:111], 0
	v_mov_b64_e32 v[112:113], 0
	v_mov_b64_e32 v[114:115], 0
	v_mov_b64_e32 v[116:117], 0
	v_mov_b64_e32 v[118:119], 0
	v_mov_b64_e32 v[120:121], 0
	v_mov_b64_e32 v[122:123], 0
	v_mov_b64_e32 v[124:125], 0
	v_mov_b64_e32 v[126:127], 0
	v_mov_b64_e32 v[128:129], 0
	s_addc_u32 s72, s51, 0
	s_mov_b32 s73, -2

;     __device__ bool next(int i, Unit& u) const { if (hot) { if (i >= rounds) return false; u.pm = (c % 8) * 2 + ((c / 8) & 1); u.pn = ((c / 8) >> 1) & 3; return true; } return so.next(i, u); }
;     ...
;         const bool has_next = S.next(ui + 1, nxt);
;         const char* nA = has_next ? (const char*)g.A + (size_t)nxt.pm * tstep : cA; const char* nB = has_next ? (const char*)g.Bt + (size_t)nxt.pn * tstep : cB;
;         for (int t = 0; t < nt; t += 2) {
;             const bool last = (t == nt - 2);
;             const char* a1 = cA + (size_t)(t + 1) * kstep;
;             const char* a2 = last ? nA : cA + (size_t)(t + 2) * kstep; const char* b2 = last ? nB : cB + (size_t)(t + 2) * kstep;
;     ...
; #pragma unroll
;         for (int a = 0; a < 2; ++a)
; #pragma unroll
;             for (int b = 0; b < 2; ++b)
; #pragma unroll
;                 for (int m = 0; m < 4; ++m)
; #pragma unroll
;                     for (int n = 0; n < 2; ++n) acc[a][b][m][n] = (f32x4){0.f, 0.f, 0.f, 0.f};
.LBB0_579:
	s_ashr_i32 s45, s44, 31
	s_lshl_b64 s[16:17], s[44:45], 19
	s_add_u32 s46, s97, s16
	s_addc_u32 s47, s29, s17
	s_and_b64 s[16:17], s[40:41], exec
	s_cselect_b32 s16, s47, s51
	s_cselect_b32 s17, s46, s50
	s_ashr_i32 s43, s42, 31
	s_lshl_b64 s[48:49], s[42:43], 19
	s_add_u32 s48, s23, s48
	s_addc_u32 s49, s56, s49
	s_and_b64 s[54:55], s[40:41], exec
	s_cselect_b32 s43, s49, s53
	s_cselect_b32 s45, s48, s52
	s_add_u32 s50, s50, 0x40080
	s_addc_u32 s51, s51, 0
	s_add_u32 s73, s52, 0x100
	v_mov_b64_e32 v[2:3], 0
	v_mov_b64_e32 v[4:5], 0
	v_mov_b64_e32 v[6:7], 0
	v_mov_b64_e32 v[8:9], 0
	v_mov_b64_e32 v[10:11], 0
	v_mov_b64_e32 v[12:13], 0
	v_mov_b64_e32 v[14:15], 0
	v_mov_b64_e32 v[16:17], 0
	v_mov_b64_e32 v[18:19], 0
	v_mov_b64_e32 v[20:21], 0
	v_mov_b64_e32 v[22:23], 0
	v_mov_b64_e32 v[24:25], 0
	v_mov_b64_e32 v[26:27], 0
	v_mov_b64_e32 v[28:29], 0
	v_mov_b64_e32 v[30:31], 0
	v_mov_b64_e32 v[32:33], 0
	v_mov_b64_e32 v[34:35], 0
	v_mov_b64_e32 v[36:37], 0
	v_mov_b64_e32 v[38:39], 0
	v_mov_b64_e32 v[40:41], 0
	v_mov_b64_e32 v[42:43], 0
	v_mov_b64_e32 v[44:45], 0
	v_mov_b64_e32 v[46:47], 0
	v_mov_b64_e32 v[48:49], 0
	v_mov_b64_e32 v[50:51], 0
	v_mov_b64_e32 v[52:53], 0
	v_mov_b64_e32 v[54:55], 0
	v_mov_b64_e32 v[56:57], 0
	v_mov_b64_e32 v[58:59], 0
	v_mov_b64_e32 v[60:61], 0
	v_mov_b64_e32 v[62:63], 0
	v_mov_b64_e32 v[64:65], 0
	v_mov_b64_e32 v[66:67], 0
	v_mov_b64_e32 v[68:69], 0
	v_mov_b64_e32 v[70:71], 0
	v_mov_b64_e32 v[72:73], 0
	v_mov_b64_e32 v[74:75], 0
	v_mov_b64_e32 v[76:77], 0
	v_mov_b64_e32 v[78:79], 0
	v_mov_b64_e32 v[80:81], 0
	v_mov_b64_e32 v[82:83], 0
	v_mov_b64_e32 v[84:85], 0
	v_mov_b64_e32 v[86:87], 0
	v_mov_b64_e32 v[88:89], 0
	v_mov_b64_e32 v[90:91], 0
	v_mov_b64_e32 v[92:93], 0
	v_mov_b64_e32 v[94:95], 0
	v_mov_b64_e32 v[96:97], 0
	v_mov_b64_e32 v[98:99], 0
	v_mov_b64_e32 v[100:101], 0
	v_mov_b64_e32 v[102:103], 0
	v_mov_b64_e32 v[104:105], 0
	v_mov_b64_e32 v[106:107], 0
	v_mov_b64_e32 v[108:109], 0
	v_mov_b64_e32 v[110:111], 0
	v_mov_b64_e32 v[112:113], 0
	v_mov_b64_e32 v[114:115], 0
	v_mov_b64_e32 v[116:117], 0
	v_mov_b64_e32 v[118:119], 0
	v_mov_b64_e32 v[120:121], 0
	v_mov_b64_e32 v[122:123], 0
	v_mov_b64_e32 v[124:125], 0
	v_mov_b64_e32 v[126:127], 0
	v_mov_b64_e32 v[128:129], 0
	s_addc_u32 s76, s53, 0
	s_mov_b32 vcc_lo, -2

;     ...
; #pragma unroll
;         for (int a = 0; a < 2; ++a)
; #pragma unroll
;             for (int b = 0; b < 2; ++b)
; #pragma unroll
;                 for (int m = 0; m < 4; ++m)
; #pragma unroll
;                     for (int n = 0; n < 2; ++n) acc[a][b][m][n] = (f32x4){0.f, 0.f, 0.f, 0.f};
.LBB0_655:
	s_add_u32 s16, s48, 0x100
	v_mov_b64_e32 v[2:3], 0
	v_mov_b64_e32 v[4:5], 0
	v_mov_b64_e32 v[6:7], 0
	v_mov_b64_e32 v[8:9], 0
	v_mov_b64_e32 v[10:11], 0
	v_mov_b64_e32 v[12:13], 0
	v_mov_b64_e32 v[14:15], 0
	v_mov_b64_e32 v[16:17], 0
	v_mov_b64_e32 v[18:19], 0
	v_mov_b64_e32 v[20:21], 0
	v_mov_b64_e32 v[22:23], 0
	v_mov_b64_e32 v[24:25], 0
	v_mov_b64_e32 v[26:27], 0
	v_mov_b64_e32 v[28:29], 0
	v_mov_b64_e32 v[30:31], 0
	v_mov_b64_e32 v[32:33], 0
	v_mov_b64_e32 v[34:35], 0
	v_mov_b64_e32 v[36:37], 0
	v_mov_b64_e32 v[38:39], 0
	v_mov_b64_e32 v[40:41], 0
	v_mov_b64_e32 v[42:43], 0
	v_mov_b64_e32 v[44:45], 0
	v_mov_b64_e32 v[46:47], 0
	v_mov_b64_e32 v[48:49], 0
	v_mov_b64_e32 v[50:51], 0
	v_mov_b64_e32 v[52:53], 0
	v_mov_b64_e32 v[54:55], 0
	v_mov_b64_e32 v[56:57], 0
	v_mov_b64_e32 v[58:59], 0
	v_mov_b64_e32 v[60:61], 0
	v_mov_b64_e32 v[62:63], 0
	v_mov_b64_e32 v[64:65], 0
	v_mov_b64_e32 v[66:67], 0
	v_mov_b64_e32 v[68:69], 0
	v_mov_b64_e32 v[70:71], 0
	v_mov_b64_e32 v[72:73], 0
	v_mov_b64_e32 v[74:75], 0
	v_mov_b64_e32 v[76:77], 0
	v_mov_b64_e32 v[78:79], 0
	v_mov_b64_e32 v[80:81], 0
	v_mov_b64_e32 v[82:83], 0
	v_mov_b64_e32 v[84:85], 0
	v_mov_b64_e32 v[86:87], 0
	v_mov_b64_e32 v[88:89], 0
	v_mov_b64_e32 v[90:91], 0
	v_mov_b64_e32 v[92:93], 0
	v_mov_b64_e32 v[94:95], 0
	v_mov_b64_e32 v[96:97], 0
	v_mov_b64_e32 v[98:99], 0
	v_mov_b64_e32 v[100:101], 0
	v_mov_b64_e32 v[102:103], 0
	v_mov_b64_e32 v[104:105], 0
	v_mov_b64_e32 v[106:107], 0
	v_mov_b64_e32 v[108:109], 0
	v_mov_b64_e32 v[110:111], 0
	v_mov_b64_e32 v[112:113], 0
	v_mov_b64_e32 v[114:115], 0
	v_mov_b64_e32 v[116:117], 0
	v_mov_b64_e32 v[118:119], 0
	v_mov_b64_e32 v[120:121], 0
	v_mov_b64_e32 v[122:123], 0
	v_mov_b64_e32 v[124:125], 0
	v_mov_b64_e32 v[126:127], 0
	v_mov_b64_e32 v[128:129], 0
	s_addc_u32 s17, s49, 0
	s_mov_b32 s73, -2
